# g23 + P1 in-projection GEMM tiles also distributed dynamically per XCD (linear per-XCD atomic tile counter, prefetch at tile start, LDS broadcast at latch)
# speedup vs baseline: 1.0218x; 1.0152x over previous
; DI int tidx() { int t = __builtin_amdgcn_workitem_id_x(); asm volatile("" : "+v"(t)); return t; }
; DI unsigned xb_ld(unsigned* p) { return __hip_atomic_load(p, __ATOMIC_RELAXED, __HIP_MEMORY_SCOPE_AGENT); }
; #define DUP(k, stmt) if (DUP_PHASE == k) { stmt; xcd_barrier(xb); }
; DI void phase1(const Params& p, const Sched& sched, unsigned char* smem) {
;   const u16* W = (const u16*)(p.ws + OFF_WIN);
;   XBlk xl{(const u16*)(p.ws + OFF_HBUF), Tn};
;   for_tiles_st(256, ZC / 128, sched, [&](int tm, int tn) {
;     const int f0 = tn * 128, t0 = tm * 256;
; __global__ void __launch_bounds__(256, 2) mega_kernel(Params p) {
;     ...
;   if (tidx() == 0) {
;     unsigned dense = 0;
;     for (unsigned j = 0; j < 16; ++j) { const unsigned c = xb_ld(&xb.bar[XB_XCNT(j)]); if (j < xb.x && c > 0u) ++dense; }
;     xb_words.w = dense;
;   }
;   __syncthreads();
;   const Sched sched{(int)xb_words.w, (int)xb_words.z, (int)xb_words.x, (int)xb_words.y};
;   DUP(1, phase1(p, sched, smem))
;   phase1(p, sched, smem); xcd_barrier(xb);
.LBB0_262:
	s_or_b64 exec, exec, s[30:31]
	v_mov_b32_e32 v0, 0x12200
	s_waitcnt lgkmcnt(0)
	s_barrier
	ds_read_b128 v[0:3], v0
	s_waitcnt lgkmcnt(0)
	v_readfirstlane_b32 s1, v2
	s_nop 1
	v_writelane_b32 v245, s1, 31
	v_readfirstlane_b32 s1, v0
	v_readfirstlane_b32 s0, v3
	s_cmpk_gt_i32 s0, 0x9f
	v_writelane_b32 v245, s1, 32
	v_writelane_b32 v245, s0, 33
	v_readfirstlane_b32 s0, v1
	s_nop 1
	v_writelane_b32 v245, s0, 34
	s_cbranch_scc1 .LBB0_281
	s_add_u32 s6, s42, 0x50000
	s_addc_u32 s7, s43, 0
	s_add_u32 s8, s42, 0x3f00800
	s_addc_u32 s9, s43, 0
	v_readlane_b32 s14, v245, 31
	s_cmp_lt_i32 s14, 64
	s_cselect_b64 s[0:1], -1, 0
	s_add_u32 s10, s42, 0x1bb00800
	s_addc_u32 s11, s43, 0
	s_add_u32 s12, s42, 0xbb00800
	s_addc_u32 s13, s43, 0
	s_lshl_b32 s30, s14, 5
	v_readlane_b32 s14, v245, 32
	s_lshl_b32 s31, s14, 5
	v_readlane_b32 s52, v245, 33
	v_readlane_b32 s14, v245, 34
	v_cndmask_b32_e64 v0, 0, 1, s[0:1]
	s_mov_b64 s[4:5], 0x50000
	s_lshl_b32 s33, s52, 3
	s_lshl_b32 s34, s14, 3
	v_cmp_ne_u32_e64 s[0:1], 1, v0
	s_movk_i32 s35, 0xf400
	s_mov_b32 s36, 0x23b00800
	s_movk_i32 s37, 0xc0
	s_movk_i32 s44, 0x80
	v_mov_b32_e32 v153, 0
	s_mov_b32 s45, 0xa0000
	s_mov_b32 s46, 0x4300000
	s_mov_b64 s[14:15], 0x400000
	s_movk_i32 s47, 0xfc00
	s_mov_b32 s48, 0x13b00800
	s_movk_i32 s49, 0xf600
	s_mov_b32 s50, 0x1fb00800
	s_movk_i32 s51, 0x110
	v_readlane_b32 s98, v245, 31
	s_mov_b32 s52, -1
	s_nop 3
	s_branch .Lp1_dyn_decode_n

; DI int tidx() { int t = __builtin_amdgcn_workitem_id_x(); asm volatile("" : "+v"(t)); return t; }
; DI void store4(u16* dst, f32x4 v) { uint2 w; w.x = cvtpk(v[0], v[1]); w.y = cvtpk(v[2], v[3]); *(uint2*)dst = w; }
; template <class F> DI void for_tiles_st(int ntm, int ntn, const Sched& sc, F f) {
;     ...
;       const int sm = sp / nsn, sn = sp - sm * nsn;
;       for (int qq = sc.rank; qq < 64; qq += sc.nloc) f(sm * 8 + (qq >> 3), sn * 8 + (qq & 7));
; DI void phase1(const Params& p, const Sched& sched, unsigned char* smem) {
;     ...
;       constexpr int EST = 136;
;       u16* Ls = (u16*)smem;
;       __syncthreads();
; #pragma unroll
;       for (int mi = 0; mi < 4; ++mi)
; #pragma unroll
;         for (int ni = 0; ni < 8; ++ni) store4(Ls + (wt * 128 + ni * 16 + lr) * EST + wf * 64 + mi * 16 + lq * 4, acc[mi][ni]);
;       __syncthreads();
;       const int tid = tidx();
; #pragma unroll
;       for (int i = 0; i < 16; ++i) {
;         const int c = tid + 256 * i, row = c >> 4, ch = (c & 15) * 8;
;         *(u32x4*)(dst + (size_t)(t0 + row) * ld + (f0 - cb) + ch) = *(const u32x4*)(Ls + row * EST + ch);
;       }
.Lp1_dyn_recompute:
	s_mul_hi_i32 s16, s52, 0x66666667
	s_lshr_b32 s17, s16, 31
	s_ashr_i32 s16, s16, 1
	s_add_i32 s22, s16, s17
	s_mul_i32 s16, s22, -5
	s_add_i32 s16, s16, s52
	s_lshl_b32 s53, s16, 3
	s_lshl_b32 s54, s22, 11
	s_cmp_lt_u32 s53, 16
	s_cselect_b64 s[16:17], -1, 0
	s_cmp_lt_u32 s53, 24
	s_cselect_b64 s[18:19], -1, 0
	s_cmp_lt_u32 s53, 32
	s_cselect_b64 s[20:21], -1, 0
	s_and_b64 s[20:21], s[20:21], exec
	s_cselect_b32 s20, s36, 0x2bb00800
	s_cselect_b32 s55, s35, 0xfffff000
	s_add_u32 s20, s42, s20
	s_mul_i32 s22, s22, 40
	s_addc_u32 s21, s43, 0
	s_sub_i32 s56, s33, s22
	s_branch .LBB0_268
.LBB0_267:
	s_or_b64 exec, exec, s[26:27]
	v_mul_u32_u24_e32 v129, 0x88, v160
	v_lshlrev_b32_e32 v128, 1, v159
	v_lshlrev_b32_e32 v129, 1, v129
	v_add3_u32 v128, v128, v158, v129
	v_cvt_pk_bf16_f32 v28, v28, v29
	v_cvt_pk_bf16_f32 v29, v30, v31
	v_cvt_pk_bf16_f32 v0, v0, v1
	v_cvt_pk_bf16_f32 v1, v2, v3
	v_cvt_pk_bf16_f32 v72, v72, v73
	v_cvt_pk_bf16_f32 v73, v74, v75
	v_add_u32_e32 v74, 0x1000, v128
	v_cvt_pk_bf16_f32 v30, v32, v33
	v_cvt_pk_bf16_f32 v31, v34, v35
	ds_write2_b64 v128, v[28:29], v[0:1] offset0:8 offset1:12
	v_cvt_pk_bf16_f32 v0, v4, v5
	v_cvt_pk_bf16_f32 v1, v6, v7
	v_cvt_pk_bf16_f32 v116, v116, v117
	v_cvt_pk_bf16_f32 v117, v118, v119
	v_cvt_pk_bf16_f32 v64, v64, v65
	v_cvt_pk_bf16_f32 v65, v66, v67
	v_add_u32_e32 v66, 0x2000, v128
	v_cvt_pk_bf16_f32 v32, v40, v41
	v_cvt_pk_bf16_f32 v33, v42, v43
	ds_write2_b64 v74, v[30:31], v[0:1] offset0:40 offset1:44
	v_cvt_pk_bf16_f32 v0, v8, v9
	v_cvt_pk_bf16_f32 v1, v10, v11
	v_cvt_pk_bf16_f32 v112, v112, v113
	v_cvt_pk_bf16_f32 v113, v114, v115
	ds_write2_b64 v66, v[116:117], v[64:65] offset0:64 offset1:68
	v_cvt_pk_bf16_f32 v64, v68, v69
	v_cvt_pk_bf16_f32 v65, v70, v71
	v_add_u32_e32 v67, 0x3000, v128
	v_cvt_pk_bf16_f32 v34, v44, v45
	v_cvt_pk_bf16_f32 v35, v46, v47
	ds_write2_b64 v66, v[32:33], v[0:1] offset0:72 offset1:76
	v_cvt_pk_bf16_f32 v0, v12, v13
	v_cvt_pk_bf16_f32 v1, v14, v15
	v_cvt_pk_bf16_f32 v108, v108, v109
	v_cvt_pk_bf16_f32 v109, v110, v111
	ds_write2_b64 v67, v[112:113], v[64:65] offset0:96 offset1:100
	v_cvt_pk_bf16_f32 v64, v76, v77
	v_cvt_pk_bf16_f32 v65, v78, v79
	v_add_u32_e32 v68, 0x4000, v128
	v_cvt_pk_bf16_f32 v40, v48, v49
	v_cvt_pk_bf16_f32 v41, v50, v51
	ds_write2_b64 v67, v[34:35], v[0:1] offset0:104 offset1:108
	v_cvt_pk_bf16_f32 v0, v16, v17
	v_cvt_pk_bf16_f32 v1, v18, v19
	v_cvt_pk_bf16_f32 v104, v104, v105
	v_cvt_pk_bf16_f32 v105, v106, v107
	ds_write2_b64 v68, v[108:109], v[64:65] offset0:128 offset1:132
	v_cvt_pk_bf16_f32 v64, v84, v85
	v_cvt_pk_bf16_f32 v65, v86, v87
	v_add_u32_e32 v69, 0x5000, v128
	v_cvt_pk_bf16_f32 v42, v52, v53
	v_cvt_pk_bf16_f32 v43, v54, v55
	ds_write2_b64 v68, v[40:41], v[0:1] offset0:136 offset1:140
	v_cvt_pk_bf16_f32 v0, v20, v21
	v_cvt_pk_bf16_f32 v1, v22, v23
	v_cvt_pk_bf16_f32 v100, v100, v101
	v_cvt_pk_bf16_f32 v101, v102, v103
	ds_write2_b64 v69, v[104:105], v[64:65] offset0:160 offset1:164
	v_cvt_pk_bf16_f32 v64, v88, v89
	v_cvt_pk_bf16_f32 v65, v90, v91
	v_add_u32_e32 v70, 0x6000, v128
	v_cvt_pk_bf16_f32 v44, v56, v57
	v_cvt_pk_bf16_f32 v45, v58, v59
	ds_write2_b64 v69, v[42:43], v[0:1] offset0:168 offset1:172
	v_cvt_pk_bf16_f32 v0, v24, v25
	v_cvt_pk_bf16_f32 v1, v26, v27
	v_cvt_pk_bf16_f32 v124, v124, v125
	v_cvt_pk_bf16_f32 v125, v126, v127
	v_cvt_pk_bf16_f32 v120, v120, v121
	v_cvt_pk_bf16_f32 v121, v122, v123
	v_cvt_pk_bf16_f32 v96, v96, v97
	v_cvt_pk_bf16_f32 v97, v98, v99
	v_cvt_pk_bf16_f32 v80, v80, v81
	v_cvt_pk_bf16_f32 v81, v82, v83
	ds_write2_b64 v70, v[100:101], v[64:65] offset0:192 offset1:196
	v_cvt_pk_bf16_f32 v64, v92, v93
	v_cvt_pk_bf16_f32 v65, v94, v95
	v_add_u32_e32 v71, 0x7000, v128
	v_cvt_pk_bf16_f32 v46, v60, v61
	v_cvt_pk_bf16_f32 v47, v62, v63
	ds_write2_b64 v70, v[44:45], v[0:1] offset0:200 offset1:204
	v_cvt_pk_bf16_f32 v0, v36, v37
	v_cvt_pk_bf16_f32 v1, v38, v39
	v_mov_b32_e32 v10, v218
	ds_write2_b64 v128, v[124:125], v[80:81] offset1:4
	ds_write2_b64 v74, v[120:121], v[72:73] offset0:32 offset1:36
	ds_write2_b64 v71, v[96:97], v[64:65] offset0:224 offset1:228
	ds_write2_b64 v71, v[46:47], v[0:1] offset0:232 offset1:236
	s_waitcnt lgkmcnt(0)
	s_barrier
	s_lshl_b32 s25, s61, 7
	v_lshlrev_b32_e32 v0, 4, v10
	v_and_b32_e32 v152, 0xf0, v0
	v_ashrrev_i32_e32 v4, 4, v10
	v_mad_u64_u32 v[0:1], s[26:27], v4, s51, v[152:153]
	v_add_u32_e32 v4, s60, v4
	v_mad_i64_i32 v[4:5], s[26:27], s24, v4, 0
	s_add_i32 s26, s62, s25
	s_ashr_i32 s27, s26, 31
	ds_read_b128 v[0:3], v0
	v_lshl_add_u64 v[4:5], v[4:5], 1, s[22:23]
	s_lshl_b64 s[26:27], s[26:27], 1
	v_lshl_add_u64 v[4:5], v[4:5], 0, s[26:27]
	v_lshl_add_u64 v[8:9], v[4:5], 0, v[152:153]
	v_add_u32_e32 v4, 0x100, v10
	v_ashrrev_i32_e32 v11, 4, v4
	v_mad_u64_u32 v[4:5], s[28:29], v11, s51, v[152:153]
	ds_read_b128 v[4:7], v4
	s_waitcnt lgkmcnt(1)
	global_store_dwordx4 v[8:9], v[0:3], off
	s_add_i32 s58, s58, s31
	s_nop 0
	v_add_u32_e32 v0, s60, v11
	v_mad_i64_i32 v[0:1], s[28:29], s24, v0, 0
	v_lshl_add_u64 v[0:1], v[0:1], 1, s[22:23]
	v_lshl_add_u64 v[0:1], v[0:1], 0, s[26:27]
	v_lshl_add_u64 v[0:1], v[0:1], 0, v[152:153]
	s_waitcnt lgkmcnt(0)
	global_store_dwordx4 v[0:1], v[4:7], off
	v_add_u32_e32 v0, 0x200, v10
	s_nop 0
	v_ashrrev_i32_e32 v4, 4, v0
	v_mad_u64_u32 v[0:1], s[28:29], v4, s51, v[152:153]
	v_add_u32_e32 v4, s60, v4
	v_mad_i64_i32 v[4:5], s[28:29], s24, v4, 0
	ds_read_b128 v[0:3], v0
	v_lshl_add_u64 v[4:5], v[4:5], 1, s[22:23]
	v_lshl_add_u64 v[4:5], v[4:5], 0, s[26:27]
	v_lshl_add_u64 v[8:9], v[4:5], 0, v[152:153]
	v_add_u32_e32 v4, 0x300, v10
	v_ashrrev_i32_e32 v11, 4, v4
	v_mad_u64_u32 v[4:5], s[28:29], v11, s51, v[152:153]
	ds_read_b128 v[4:7], v4
	s_waitcnt lgkmcnt(1)
; DI int tidx() { int t = __builtin_amdgcn_workitem_id_x(); asm volatile("" : "+v"(t)); return t; }
; template <class F> DI void for_tiles_st(int ntm, int ntn, const Sched& sc, F f) {
;     ...
;     for (int sp = sc.xd; sp < nsuper; sp += sc.nx) {
;       const int sm = sp / nsn, sn = sp - sm * nsn;
;       for (int qq = sc.rank; qq < 64; qq += sc.nloc) f(sm * 8 + (qq >> 3), sn * 8 + (qq & 7));
; DI void phase1(const Params& p, const Sched& sched, unsigned char* smem) {
;     ...
;       const int tid = tidx();
; #pragma unroll
;       for (int i = 0; i < 16; ++i) {
;         const int c = tid + 256 * i, row = c >> 4, ch = (c & 15) * 8;
;         *(u32x4*)(dst + (size_t)(t0 + row) * ld + (f0 - cb) + ch) = *(const u32x4*)(Ls + row * EST + ch);
;       }
	global_store_dwordx4 v[8:9], v[0:3], off
	s_nop 1
	v_add_u32_e32 v0, s60, v11
	v_mad_i64_i32 v[0:1], s[28:29], s24, v0, 0
	v_lshl_add_u64 v[0:1], v[0:1], 1, s[22:23]
	v_lshl_add_u64 v[0:1], v[0:1], 0, s[26:27]
	v_lshl_add_u64 v[0:1], v[0:1], 0, v[152:153]
	s_waitcnt lgkmcnt(0)
	global_store_dwordx4 v[0:1], v[4:7], off
	v_add_u32_e32 v0, 0x400, v10
	s_nop 0
	v_ashrrev_i32_e32 v4, 4, v0
	v_mad_u64_u32 v[0:1], s[28:29], v4, s51, v[152:153]
	v_add_u32_e32 v4, s60, v4
	v_mad_i64_i32 v[4:5], s[28:29], s24, v4, 0
	ds_read_b128 v[0:3], v0
	v_lshl_add_u64 v[4:5], v[4:5], 1, s[22:23]
	v_lshl_add_u64 v[4:5], v[4:5], 0, s[26:27]
	v_lshl_add_u64 v[8:9], v[4:5], 0, v[152:153]
	v_add_u32_e32 v4, 0x500, v10
	v_ashrrev_i32_e32 v11, 4, v4
	v_mad_u64_u32 v[4:5], s[28:29], v11, s51, v[152:153]
	ds_read_b128 v[4:7], v4
	s_waitcnt lgkmcnt(1)
	global_store_dwordx4 v[8:9], v[0:3], off
	s_nop 1
	v_add_u32_e32 v0, s60, v11
	v_mad_i64_i32 v[0:1], s[28:29], s24, v0, 0
	v_lshl_add_u64 v[0:1], v[0:1], 1, s[22:23]
	v_lshl_add_u64 v[0:1], v[0:1], 0, s[26:27]
	v_lshl_add_u64 v[0:1], v[0:1], 0, v[152:153]
	s_waitcnt lgkmcnt(0)
	global_store_dwordx4 v[0:1], v[4:7], off
	v_add_u32_e32 v0, 0x600, v10
	s_nop 0
	v_ashrrev_i32_e32 v4, 4, v0
	v_mad_u64_u32 v[0:1], s[28:29], v4, s51, v[152:153]
	v_add_u32_e32 v4, s60, v4
	v_mad_i64_i32 v[4:5], s[28:29], s24, v4, 0
	ds_read_b128 v[0:3], v0
	v_lshl_add_u64 v[4:5], v[4:5], 1, s[22:23]
	v_lshl_add_u64 v[4:5], v[4:5], 0, s[26:27]
	v_lshl_add_u64 v[8:9], v[4:5], 0, v[152:153]
	v_add_u32_e32 v4, 0x700, v10
	v_ashrrev_i32_e32 v11, 4, v4
	v_mad_u64_u32 v[4:5], s[28:29], v11, s51, v[152:153]
	ds_read_b128 v[4:7], v4
	s_waitcnt lgkmcnt(1)
	global_store_dwordx4 v[8:9], v[0:3], off
	s_nop 1
	v_add_u32_e32 v0, s60, v11
	v_mad_i64_i32 v[0:1], s[28:29], s24, v0, 0
	v_lshl_add_u64 v[0:1], v[0:1], 1, s[22:23]
	v_lshl_add_u64 v[0:1], v[0:1], 0, s[26:27]
	v_lshl_add_u64 v[0:1], v[0:1], 0, v[152:153]
	s_waitcnt lgkmcnt(0)
	global_store_dwordx4 v[0:1], v[4:7], off
	v_add_u32_e32 v0, 0x800, v10
	s_nop 0
	v_ashrrev_i32_e32 v4, 4, v0
	v_mad_u64_u32 v[0:1], s[28:29], v4, s51, v[152:153]
	v_add_u32_e32 v4, s60, v4
	v_mad_i64_i32 v[4:5], s[28:29], s24, v4, 0
	ds_read_b128 v[0:3], v0
	v_lshl_add_u64 v[4:5], v[4:5], 1, s[22:23]
	v_lshl_add_u64 v[4:5], v[4:5], 0, s[26:27]
	v_lshl_add_u64 v[8:9], v[4:5], 0, v[152:153]
	v_add_u32_e32 v4, 0x900, v10
	v_ashrrev_i32_e32 v11, 4, v4
	v_mad_u64_u32 v[4:5], s[28:29], v11, s51, v[152:153]
	ds_read_b128 v[4:7], v4
	s_waitcnt lgkmcnt(1)
	global_store_dwordx4 v[8:9], v[0:3], off
	s_nop 1
	v_add_u32_e32 v0, s60, v11
	v_mad_i64_i32 v[0:1], s[28:29], s24, v0, 0
	v_lshl_add_u64 v[0:1], v[0:1], 1, s[22:23]
	v_lshl_add_u64 v[0:1], v[0:1], 0, s[26:27]
	v_lshl_add_u64 v[0:1], v[0:1], 0, v[152:153]
	s_waitcnt lgkmcnt(0)
	global_store_dwordx4 v[0:1], v[4:7], off
	v_add_u32_e32 v0, 0xa00, v10
	s_nop 0
	v_ashrrev_i32_e32 v4, 4, v0
	v_mad_u64_u32 v[0:1], s[28:29], v4, s51, v[152:153]
	v_add_u32_e32 v4, s60, v4
	v_mad_i64_i32 v[4:5], s[28:29], s24, v4, 0
	ds_read_b128 v[0:3], v0
	v_lshl_add_u64 v[4:5], v[4:5], 1, s[22:23]
	v_lshl_add_u64 v[4:5], v[4:5], 0, s[26:27]
	v_lshl_add_u64 v[8:9], v[4:5], 0, v[152:153]
	v_add_u32_e32 v4, 0xb00, v10
	v_ashrrev_i32_e32 v11, 4, v4
	v_mad_u64_u32 v[4:5], s[28:29], v11, s51, v[152:153]
	ds_read_b128 v[4:7], v4
	s_waitcnt lgkmcnt(1)
	global_store_dwordx4 v[8:9], v[0:3], off
	s_nop 1
	v_add_u32_e32 v0, s60, v11
	v_mad_i64_i32 v[0:1], s[28:29], s24, v0, 0
	v_lshl_add_u64 v[0:1], v[0:1], 1, s[22:23]
	v_lshl_add_u64 v[0:1], v[0:1], 0, s[26:27]
	v_lshl_add_u64 v[0:1], v[0:1], 0, v[152:153]
	s_waitcnt lgkmcnt(0)
	global_store_dwordx4 v[0:1], v[4:7], off
	v_add_u32_e32 v0, 0xc00, v10
	s_nop 0
	v_ashrrev_i32_e32 v4, 4, v0
	v_mad_u64_u32 v[0:1], s[28:29], v4, s51, v[152:153]
	v_add_u32_e32 v4, s60, v4
	v_mad_i64_i32 v[4:5], s[28:29], s24, v4, 0
	ds_read_b128 v[0:3], v0
	v_lshl_add_u64 v[4:5], v[4:5], 1, s[22:23]
	v_lshl_add_u64 v[4:5], v[4:5], 0, s[26:27]
	v_lshl_add_u64 v[8:9], v[4:5], 0, v[152:153]
	v_add_u32_e32 v4, 0xd00, v10
	v_ashrrev_i32_e32 v11, 4, v4
	v_mad_u64_u32 v[4:5], s[28:29], v11, s51, v[152:153]
	ds_read_b128 v[4:7], v4
	s_waitcnt lgkmcnt(1)
	global_store_dwordx4 v[8:9], v[0:3], off
	s_nop 1
	v_add_u32_e32 v0, s60, v11
	v_mad_i64_i32 v[0:1], s[28:29], s24, v0, 0
	v_lshl_add_u64 v[0:1], v[0:1], 1, s[22:23]
	v_lshl_add_u64 v[0:1], v[0:1], 0, s[26:27]
	v_lshl_add_u64 v[0:1], v[0:1], 0, v[152:153]
	s_waitcnt lgkmcnt(0)
	global_store_dwordx4 v[0:1], v[4:7], off
	v_add_u32_e32 v0, 0xe00, v10
	s_nop 0
	v_ashrrev_i32_e32 v4, 4, v0
	v_mad_u64_u32 v[0:1], s[28:29], v4, s51, v[152:153]
	v_add_u32_e32 v4, s60, v4
	v_mad_i64_i32 v[4:5], s[28:29], s24, v4, 0
	ds_read_b128 v[0:3], v0
	v_lshl_add_u64 v[4:5], v[4:5], 1, s[22:23]
	v_lshl_add_u64 v[4:5], v[4:5], 0, s[26:27]
	v_lshl_add_u64 v[8:9], v[4:5], 0, v[152:153]
	v_add_u32_e32 v4, 0xf00, v10
	v_ashrrev_i32_e32 v10, 4, v4
	v_mad_u64_u32 v[4:5], s[28:29], v10, s51, v[152:153]
	ds_read_b128 v[4:7], v4
	s_waitcnt lgkmcnt(1)
	global_store_dwordx4 v[8:9], v[0:3], off
	s_nop 1
	v_add_u32_e32 v0, s60, v10
	v_mad_i64_i32 v[0:1], s[24:25], s24, v0, 0
	v_lshl_add_u64 v[0:1], v[0:1], 1, s[22:23]
	v_readlane_b32 s22, v245, 32
	v_lshl_add_u64 v[0:1], v[0:1], 0, s[26:27]
	v_lshl_add_u64 v[0:1], v[0:1], 0, v[152:153]
	s_waitcnt lgkmcnt(0)
	global_store_dwordx4 v[0:1], v[4:7], off
	v_mov_b32_e32 v243, 0x12000
	v_readfirstlane_b32 s98, v218
	s_cmp_lg_u32 s98, 0
	s_cbranch_scc1 .Lp1_dyn_skip_b
	s_waitcnt vmcnt(16)
	s_mov_b64 s[100:101], exec
	s_mov_b64 exec, 1
	ds_write_b32 v243, v240
	s_waitcnt lgkmcnt(0)
	s_mov_b64 exec, s[100:101]
.Lp1_dyn_skip_b:
	s_barrier
	ds_read_b32 v240, v243
	s_waitcnt lgkmcnt(0)
	v_readfirstlane_b32 s98, v240
	v_readlane_b32 s99, v245, 32
	s_nop 3
	s_add_i32 s98, s98, s99
.Lp1_dyn_decode_n:
	s_and_b32 s59, s98, 63
	s_mov_b32 s57, s59
	s_lshl_b32 s58, s59, 5
	s_lshr_b32 s98, s98, 6
	v_readlane_b32 s99, v245, 34
	s_nop 3
	s_mul_i32 s98, s98, s99
	v_readlane_b32 s99, v245, 33
	s_nop 3
	s_add_i32 s98, s98, s99
	s_cmpk_gt_i32 s98, 0x9f
	s_cbranch_scc1 .LBB0_281
	s_cmp_eq_u32 s98, s52
	s_cbranch_scc1 .LBB0_268
	s_mov_b32 s52, s98
	s_lshl_b32 s33, s52, 3
	s_branch .Lp1_dyn_recompute
.LBB0_268:
	v_readfirstlane_b32 s22, v218
	s_cmp_lg_u32 s22, 0
	s_cbranch_scc1 .Lp1_dyn_skip_a
	s_mov_b64 s[100:101], exec
	s_mov_b64 exec, 1
	v_readlane_b32 s22, v245, 33
	v_mov_b32_e32 v241, 0x3fb04300
	v_mov_b32_e32 v242, 1
	s_nop 1
	v_lshl_add_u32 v241, s22, 6, v241
	global_atomic_add v240, v241, v242, s[42:43] sc0
	s_mov_b64 exec, s[100:101]
